# sample_gemm_resid epilogue: four residual loads issued together instead of serialised behind write-through stores
# speedup vs baseline: 1.0000x; 1.0000x over previous
.LBB0_36:
	s_and_b32 s9, s7, 62
	s_or_b32 s10, s9, s4
	s_ashr_i32 s9, s8, 1
	s_and_b32 s9, s9, -16
	s_addk_i32 s9, 0x4000
	v_or_b32_e32 v0, s9, v147
	v_ashrrev_i32_e32 v1, 31, v0
	v_lshlrev_b64 v[0:1], 11, v[0:1]
	v_lshl_or_b32 v23, s10, 4, v147
	v_lshl_add_u64 v[32:33], v[16:17], 0, v[0:1]
	v_lshlrev_b32_e32 v144, 11, v23
	v_lshl_add_u64 v[34:35], v[18:19], 0, v[144:145]
	global_load_dwordx4 v[0:3], v[32:33], off
	global_load_dwordx4 v[4:7], v[34:35], off
	global_load_dwordx4 v[8:11], v[32:33], off offset:64
	global_load_dwordx4 v[12:15], v[34:35], off offset:64
	s_andn2_b64 vcc, exec, s[0:1]
	s_waitcnt vmcnt(0)
	v_mfma_f32_16x16x32_bf16 v[0:3], v[0:3], v[4:7], 0
	s_waitcnt vmcnt(0)
	v_mfma_f32_16x16x32_bf16 v[4:7], v[8:11], v[12:15], 0
	global_load_dwordx4 v[8:11], v[32:33], off offset:128
	global_load_dwordx4 v[12:15], v[34:35], off offset:128
	global_load_dwordx4 v[24:27], v[32:33], off offset:192
	global_load_dwordx4 v[28:31], v[34:35], off offset:192
	s_waitcnt vmcnt(2)
	v_mfma_f32_16x16x32_bf16 v[0:3], v[8:11], v[12:15], v[0:3]
	s_waitcnt vmcnt(0)
	v_mfma_f32_16x16x32_bf16 v[4:7], v[24:27], v[28:31], v[4:7]
	global_load_dwordx4 v[8:11], v[32:33], off offset:256
	global_load_dwordx4 v[12:15], v[34:35], off offset:256
	global_load_dwordx4 v[24:27], v[32:33], off offset:320
	global_load_dwordx4 v[28:31], v[34:35], off offset:320
	s_waitcnt vmcnt(2)
	v_mfma_f32_16x16x32_bf16 v[0:3], v[8:11], v[12:15], v[0:3]
	s_waitcnt vmcnt(0)
	v_mfma_f32_16x16x32_bf16 v[4:7], v[24:27], v[28:31], v[4:7]
	global_load_dwordx4 v[8:11], v[32:33], off offset:384
	global_load_dwordx4 v[12:15], v[34:35], off offset:384
	global_load_dwordx4 v[24:27], v[32:33], off offset:448
	global_load_dwordx4 v[28:31], v[34:35], off offset:448
	s_barrier
	s_waitcnt vmcnt(2)
	v_mfma_f32_16x16x32_bf16 v[0:3], v[8:11], v[12:15], v[0:3]
	s_waitcnt vmcnt(0)
	v_mfma_f32_16x16x32_bf16 v[4:7], v[24:27], v[28:31], v[4:7]
	s_nop 7
	v_pk_add_f32 v[2:3], v[2:3], v[6:7]
	v_pk_add_f32 v[0:1], v[0:1], v[4:5]
	ds_write_b128 v20, v[0:3]
	s_waitcnt lgkmcnt(0)
	s_barrier
	s_cbranch_vccnz .LBB0_35
	v_or_b32_e32 v24, s9, v22
	v_ashrrev_i32_e32 v25, 31, v24
	v_lshlrev_b64 v[26:27], 12, v[24:25]
	v_lshlrev_b32_e32 v23, 2, v23
	v_readlane_b32 s10, v250, 4
	v_or_b32_e32 v26, v26, v23
	v_readlane_b32 s11, v250, 5
	ds_read_b128 v[12:15], v21
	ds_read_b128 v[4:7], v21 offset:2048
	ds_read_b128 v[0:3], v21 offset:4096
	ds_read_b128 v[8:11], v21 offset:6144
	v_lshl_add_u64 v[28:29], s[10:11], 0, v[26:27]
	v_lshl_add_u64 v[26:27], s[66:67], 0, v[26:27]
	global_load_dword v25, v[26:27], off
	v_or_b32_e32 v242, 1, v24
	v_ashrrev_i32_e32 v243, 31, v242
	v_lshlrev_b64 v[242:243], 12, v[242:243]
	v_or_b32_e32 v242, v242, v23
	v_lshl_add_u64 v[242:243], s[66:67], 0, v[242:243]
	global_load_dword v246, v[242:243], off
	v_or_b32_e32 v242, 2, v24
	v_ashrrev_i32_e32 v243, 31, v242
	v_lshlrev_b64 v[242:243], 12, v[242:243]
	v_or_b32_e32 v242, v242, v23
	v_lshl_add_u64 v[242:243], s[66:67], 0, v[242:243]
	global_load_dword v247, v[242:243], off
	v_or_b32_e32 v242, 3, v24
	v_ashrrev_i32_e32 v243, 31, v242
	v_lshlrev_b64 v[242:243], 12, v[242:243]
	v_or_b32_e32 v242, v242, v23
	v_lshl_add_u64 v[242:243], s[66:67], 0, v[242:243]
	global_load_dword v248, v[242:243], off
	s_waitcnt lgkmcnt(3)
	v_mov_b32_e32 v26, v12
	s_waitcnt lgkmcnt(1)
	v_mov_b32_e32 v27, v0
	v_mov_b32_e32 v30, v4
	s_waitcnt lgkmcnt(0)
	v_mov_b32_e32 v31, v8
	v_pk_add_f32 v[26:27], v[26:27], v[30:31]
	v_mov_b32_e32 v8, v5
	v_add_f32_e32 v0, v26, v27
	v_or_b32_e32 v26, 1, v24
	v_ashrrev_i32_e32 v27, 31, v26
	v_lshlrev_b64 v[26:27], 12, v[26:27]
	v_or_b32_e32 v26, v26, v23
	s_nop 0
	s_waitcnt vmcnt(3)
	v_fmac_f32_e32 v0, 0x3fd744fd, v25
	global_store_dword v[28:29], v0, off sc1
	v_lshl_add_u64 v[28:29], s[10:11], 0, v[26:27]
	v_lshl_add_u64 v[26:27], s[66:67], 0, v[26:27]
	s_nop 0
	v_mov_b32_e32 v0, v13
	v_pk_add_f32 v[0:1], v[0:1], v[8:9]
	v_mov_b32_e32 v8, v6
	v_add_f32_e32 v0, v0, v1
	v_mov_b32_e32 v9, v10
	v_mov_b32_e32 v10, v7
	s_nop 0
	s_waitcnt vmcnt(3)
	v_fmac_f32_e32 v0, 0x3fd744fd, v246
	global_store_dword v[28:29], v0, off sc1
	v_or_b32_e32 v0, 2, v24
	v_ashrrev_i32_e32 v1, 31, v0
	v_lshlrev_b64 v[0:1], 12, v[0:1]
	v_or_b32_e32 v0, v0, v23
	v_lshl_add_u64 v[4:5], s[10:11], 0, v[0:1]
	v_lshl_add_u64 v[0:1], s[66:67], 0, v[0:1]
	s_nop 0
	v_mov_b32_e32 v0, v14
	v_mov_b32_e32 v1, v2
	v_pk_add_f32 v[0:1], v[0:1], v[8:9]
	v_mov_b32_e32 v2, v15
	v_add_f32_e32 v0, v0, v1
	s_nop 0
	s_waitcnt vmcnt(3)
	v_fmac_f32_e32 v0, 0x3fd744fd, v247
	global_store_dword v[4:5], v0, off sc1
	v_or_b32_e32 v0, 3, v24
	v_ashrrev_i32_e32 v1, 31, v0
	v_lshlrev_b64 v[0:1], 12, v[0:1]
	v_or_b32_e32 v0, v0, v23
	v_lshl_add_u64 v[4:5], s[10:11], 0, v[0:1]
	v_lshl_add_u64 v[0:1], s[66:67], 0, v[0:1]
	s_nop 0
	v_pk_add_f32 v[0:1], v[2:3], v[10:11]
	s_nop 0
	v_add_f32_e32 v0, v0, v1
	s_nop 0
	s_waitcnt vmcnt(3)
	v_fmac_f32_e32 v0, 0x3fd744fd, v248
	global_store_dword v[4:5], v0, off sc1
	s_branch .LBB0_35

.LBB0_392:
	s_and_b32 s4, s9, 62
	s_or_b32 s5, s4, s6
	s_ashr_i32 s4, s10, 1
	s_and_b32 s4, s4, -16
	s_addk_i32 s4, 0x4000
	v_or_b32_e32 v0, s4, v147
	s_movk_i32 s11, 0x1600
	v_lshl_or_b32 v25, s5, 4, v147
	v_mad_i64_i32 v[2:3], s[12:13], v0, s11, v[16:17]
	v_mul_u32_u24_e32 v0, 0xb00, v25
	v_lshlrev_b32_e32 v144, 1, v0
	v_lshl_add_u64 v[0:1], v[18:19], 0, v[144:145]
	global_load_dwordx4 v[4:7], v[2:3], off
	global_load_dwordx4 v[8:11], v[0:1], off
	global_load_dwordx4 v[12:15], v[2:3], off offset:64
	global_load_dwordx4 v[26:29], v[0:1], off offset:64
	s_andn2_b64 vcc, exec, s[0:1]
	s_waitcnt vmcnt(0)
	v_mfma_f32_16x16x32_bf16 v[4:7], v[4:7], v[8:11], 0
	s_waitcnt vmcnt(0)
	v_mfma_f32_16x16x32_bf16 v[8:11], v[12:15], v[26:29], 0
	global_load_dwordx4 v[12:15], v[2:3], off offset:128
	global_load_dwordx4 v[26:29], v[0:1], off offset:128
	global_load_dwordx4 v[30:33], v[2:3], off offset:192
	global_load_dwordx4 v[34:37], v[0:1], off offset:192
	s_waitcnt vmcnt(2)
	v_mfma_f32_16x16x32_bf16 v[4:7], v[12:15], v[26:29], v[4:7]
	s_waitcnt vmcnt(0)
	v_mfma_f32_16x16x32_bf16 v[8:11], v[30:33], v[34:37], v[8:11]
	global_load_dwordx4 v[12:15], v[2:3], off offset:256
	global_load_dwordx4 v[26:29], v[0:1], off offset:256
	global_load_dwordx4 v[30:33], v[2:3], off offset:320
	global_load_dwordx4 v[34:37], v[0:1], off offset:320
	s_waitcnt vmcnt(2)
	v_mfma_f32_16x16x32_bf16 v[4:7], v[12:15], v[26:29], v[4:7]
	s_waitcnt vmcnt(0)
	v_mfma_f32_16x16x32_bf16 v[8:11], v[30:33], v[34:37], v[8:11]
	global_load_dwordx4 v[12:15], v[2:3], off offset:384
	global_load_dwordx4 v[26:29], v[0:1], off offset:384
	global_load_dwordx4 v[30:33], v[2:3], off offset:448
	global_load_dwordx4 v[34:37], v[0:1], off offset:448
	s_waitcnt vmcnt(2)
	v_mfma_f32_16x16x32_bf16 v[4:7], v[12:15], v[26:29], v[4:7]
	s_waitcnt vmcnt(0)
	v_mfma_f32_16x16x32_bf16 v[8:11], v[30:33], v[34:37], v[8:11]
	global_load_dwordx4 v[12:15], v[2:3], off offset:512
	global_load_dwordx4 v[26:29], v[0:1], off offset:512
	global_load_dwordx4 v[30:33], v[2:3], off offset:576
	global_load_dwordx4 v[34:37], v[0:1], off offset:576
	s_waitcnt vmcnt(2)
	v_mfma_f32_16x16x32_bf16 v[4:7], v[12:15], v[26:29], v[4:7]
	s_waitcnt vmcnt(0)
	v_mfma_f32_16x16x32_bf16 v[8:11], v[30:33], v[34:37], v[8:11]
	global_load_dwordx4 v[12:15], v[2:3], off offset:640
	global_load_dwordx4 v[26:29], v[0:1], off offset:640
	global_load_dwordx4 v[30:33], v[2:3], off offset:704
	global_load_dwordx4 v[34:37], v[0:1], off offset:704
	s_waitcnt vmcnt(2)
	v_mfma_f32_16x16x32_bf16 v[4:7], v[12:15], v[26:29], v[4:7]
	s_waitcnt vmcnt(0)
	v_mfma_f32_16x16x32_bf16 v[8:11], v[30:33], v[34:37], v[8:11]
	global_load_dwordx4 v[12:15], v[2:3], off offset:768
	global_load_dwordx4 v[26:29], v[0:1], off offset:768
	global_load_dwordx4 v[30:33], v[2:3], off offset:832
	global_load_dwordx4 v[34:37], v[0:1], off offset:832
	s_waitcnt vmcnt(2)
	v_mfma_f32_16x16x32_bf16 v[4:7], v[12:15], v[26:29], v[4:7]
	s_waitcnt vmcnt(0)
	v_mfma_f32_16x16x32_bf16 v[8:11], v[30:33], v[34:37], v[8:11]
	global_load_dwordx4 v[12:15], v[2:3], off offset:896
	global_load_dwordx4 v[26:29], v[0:1], off offset:896
	global_load_dwordx4 v[30:33], v[2:3], off offset:960
	global_load_dwordx4 v[34:37], v[0:1], off offset:960
	s_waitcnt vmcnt(2)
	v_mfma_f32_16x16x32_bf16 v[4:7], v[12:15], v[26:29], v[4:7]
	s_waitcnt vmcnt(0)
	v_mfma_f32_16x16x32_bf16 v[8:11], v[30:33], v[34:37], v[8:11]
	global_load_dwordx4 v[12:15], v[2:3], off offset:1024
	global_load_dwordx4 v[26:29], v[0:1], off offset:1024
	global_load_dwordx4 v[30:33], v[2:3], off offset:1088
	global_load_dwordx4 v[34:37], v[0:1], off offset:1088
	s_waitcnt vmcnt(2)
	v_mfma_f32_16x16x32_bf16 v[4:7], v[12:15], v[26:29], v[4:7]
	s_waitcnt vmcnt(0)
	v_mfma_f32_16x16x32_bf16 v[8:11], v[30:33], v[34:37], v[8:11]
	global_load_dwordx4 v[12:15], v[2:3], off offset:1152
	global_load_dwordx4 v[26:29], v[0:1], off offset:1152
	global_load_dwordx4 v[30:33], v[2:3], off offset:1216
	global_load_dwordx4 v[34:37], v[0:1], off offset:1216
	s_waitcnt vmcnt(2)
	v_mfma_f32_16x16x32_bf16 v[4:7], v[12:15], v[26:29], v[4:7]
	s_waitcnt vmcnt(0)
	v_mfma_f32_16x16x32_bf16 v[8:11], v[30:33], v[34:37], v[8:11]
	global_load_dwordx4 v[12:15], v[2:3], off offset:1280
	global_load_dwordx4 v[26:29], v[0:1], off offset:1280
	global_load_dwordx4 v[30:33], v[2:3], off offset:1344
	s_nop 0
	global_load_dwordx4 v[0:3], v[0:1], off offset:1344
	s_barrier
	s_waitcnt vmcnt(2)
	v_mfma_f32_16x16x32_bf16 v[4:7], v[12:15], v[26:29], v[4:7]
	s_waitcnt vmcnt(0)
	v_mfma_f32_16x16x32_bf16 v[0:3], v[30:33], v[0:3], v[8:11]
	s_nop 7
	v_pk_add_f32 v[2:3], v[6:7], v[2:3]
	v_pk_add_f32 v[0:1], v[4:5], v[0:1]
	ds_write_b128 v22, v[0:3]
	s_waitcnt lgkmcnt(0)
	s_barrier
	s_cbranch_vccnz .LBB0_391
	v_or_b32_e32 v20, s4, v24
	v_ashrrev_i32_e32 v21, 31, v20
	v_lshlrev_b64 v[26:27], 12, v[20:21]
	v_lshlrev_b32_e32 v21, 2, v25
	v_readlane_b32 s12, v250, 4
	v_or_b32_e32 v26, v26, v21
	v_readlane_b32 s13, v250, 5
	ds_read_b128 v[12:15], v23
	ds_read_b128 v[4:7], v23 offset:2048
	ds_read_b128 v[0:3], v23 offset:4096
	ds_read_b128 v[8:11], v23 offset:6144
	v_lshl_add_u64 v[28:29], s[12:13], 0, v[26:27]
	v_lshl_add_u64 v[26:27], s[66:67], 0, v[26:27]
	global_load_dword v26, v[26:27], off
	v_or_b32_e32 v242, 1, v20
	v_ashrrev_i32_e32 v243, 31, v242
	v_lshlrev_b64 v[242:243], 12, v[242:243]
	v_or_b32_e32 v242, v242, v21
	v_lshl_add_u64 v[242:243], s[66:67], 0, v[242:243]
	global_load_dword v246, v[242:243], off
	v_or_b32_e32 v242, 2, v20
	v_ashrrev_i32_e32 v243, 31, v242
	v_lshlrev_b64 v[242:243], 12, v[242:243]
	v_or_b32_e32 v242, v242, v21
	v_lshl_add_u64 v[242:243], s[66:67], 0, v[242:243]
	global_load_dword v247, v[242:243], off
	v_or_b32_e32 v242, 3, v20
	v_ashrrev_i32_e32 v243, 31, v242
	v_lshlrev_b64 v[242:243], 12, v[242:243]
	v_or_b32_e32 v242, v242, v21
	v_lshl_add_u64 v[242:243], s[66:67], 0, v[242:243]
	global_load_dword v248, v[242:243], off
	s_waitcnt lgkmcnt(3)
	v_mov_b32_e32 v30, v12
	s_waitcnt lgkmcnt(1)
	v_mov_b32_e32 v31, v0
	v_mov_b32_e32 v32, v4
	s_waitcnt lgkmcnt(0)
	v_mov_b32_e32 v33, v8
	v_pk_add_f32 v[30:31], v[30:31], v[32:33]
	v_mov_b32_e32 v8, v5
	v_pk_add_f32 v[30:31], v[30:31], v[30:31] op_sel_hi:[0,1]
	v_mov_b32_e32 v27, v31
	v_mul_f32_e32 v0, 0.5, v31
	s_mov_b32 s4, s53
	s_mov_b32 s5, s52
	s_nop 0
	s_waitcnt vmcnt(3)
	v_pk_fma_f32 v[26:27], v[26:27], s[52:53], v[0:1] op_sel_hi:[1,1,0]
	global_store_dword v[28:29], v26, off sc1
	v_or_b32_e32 v26, 1, v20
	v_ashrrev_i32_e32 v27, 31, v26
	v_lshlrev_b64 v[26:27], 12, v[26:27]
	v_or_b32_e32 v26, v26, v21
	v_lshl_add_u64 v[28:29], s[12:13], 0, v[26:27]
	v_lshl_add_u64 v[26:27], s[66:67], 0, v[26:27]
	s_nop 0
	v_mov_b32_e32 v0, v13
	v_pk_add_f32 v[0:1], v[0:1], v[8:9]
	v_mov_b32_e32 v8, v6
	v_pk_add_f32 v[0:1], v[0:1], v[0:1] op_sel:[0,1] op_sel_hi:[1,0]
	v_mov_b32_e32 v9, v10
	v_mov_b32_e32 v10, v7
	s_nop 0
	s_waitcnt vmcnt(3)
	v_mov_b32_e32 v1, v246
	v_mul_f32_e32 v4, 0x3fd744fd, v246
	v_pk_fma_f32 v[0:1], v[0:1], s[4:5], v[4:5] op_sel_hi:[1,1,0]
	global_store_dword v[28:29], v0, off sc1
	v_or_b32_e32 v0, 2, v20
	v_ashrrev_i32_e32 v1, 31, v0
	v_lshlrev_b64 v[0:1], 12, v[0:1]
	v_or_b32_e32 v0, v0, v21
	v_lshl_add_u64 v[4:5], s[12:13], 0, v[0:1]
	v_lshl_add_u64 v[0:1], s[66:67], 0, v[0:1]
	s_nop 0
	v_mov_b32_e32 v0, v14
	v_mov_b32_e32 v1, v2
	v_pk_add_f32 v[0:1], v[0:1], v[8:9]
	s_nop 0
	s_waitcnt vmcnt(3)
	v_mul_f32_e32 v2, 0x3fd744fd, v247
	v_pk_add_f32 v[0:1], v[0:1], v[0:1] op_sel:[0,1] op_sel_hi:[1,0]
	s_nop 0
	v_mov_b32_e32 v1, v247
	v_pk_fma_f32 v[0:1], v[0:1], s[4:5], v[2:3] op_sel_hi:[1,1,0]
	global_store_dword v[4:5], v0, off sc1
	v_or_b32_e32 v0, 3, v20
	v_ashrrev_i32_e32 v1, 31, v0
	v_lshlrev_b64 v[0:1], 12, v[0:1]
	v_or_b32_e32 v0, v0, v21
	v_lshl_add_u64 v[4:5], s[12:13], 0, v[0:1]
	v_lshl_add_u64 v[0:1], s[66:67], 0, v[0:1]
	s_nop 0
	v_mov_b32_e32 v2, v15
	v_pk_add_f32 v[0:1], v[2:3], v[10:11]
	s_nop 0
	s_waitcnt vmcnt(3)
	v_mul_f32_e32 v2, 0x3fd744fd, v248
	v_pk_add_f32 v[0:1], v[0:1], v[0:1] op_sel:[0,1] op_sel_hi:[1,0]
	s_nop 0
	v_mov_b32_e32 v1, v248
	v_pk_fma_f32 v[0:1], v[0:1], s[4:5], v[2:3] op_sel_hi:[1,1,0]
	global_store_dword v[4:5], v0, off sc1
	s_branch .LBB0_391
